# v5 + batched lgkmcnt waits in the MLA inner loop (one wait per two MFMAs)
# speedup vs baseline: 1.0061x; 1.0054x over previous
.LBB0_202:
	s_add_i32 s9, s9, 2
	s_mov_b32 s11, s8
	s_mov_b32 s10, s12
	v_add_u32_e32 v242, s10, v215
	ds_read_b128 v[32:35], v242
	ds_read_b128 v[36:39], v242 offset:6656
	ds_read_b128 v[40:43], v242 offset:32
	ds_read_b128 v[44:47], v242 offset:6688
	ds_read_b128 v[238:241], v242 offset:64
	v_add_u32_e32 v243, s11, v233
	s_min_u32 s8, s9, 59
	s_lshl_b32 s8, s8, 6
	s_addk_i32 s8, 0x100
	s_lshl_b32 s76, s8, 12
	v_lshl_add_u64 v[164:165], v[206:207], 0, s[76:77]
	v_add_co_u32_e32 v172, vcc, s83, v164
	s_lshl_b32 s76, s8, 6
	s_nop 0
	v_addc_co_u32_e32 v173, vcc, 0, v165, vcc
	global_load_dwordx4 v[164:167], v[164:165], off
	v_lshl_add_u64 v[168:169], v[208:209], 0, s[76:77]
	global_load_dwordx4 v[172:175], v[172:173], off
	global_load_dwordx4 v[168:171], v[168:169], off
	v_exp_f32_e32 v80, v80
	v_exp_f32_e32 v81, v81
	v_exp_f32_e32 v82, v82
	v_add_f32_e32 v205, v205, v80
	v_exp_f32_e32 v83, v83
	v_exp_f32_e32 v84, v84
	v_add_f32_e32 v205, v205, v82
	v_exp_f32_e32 v85, v85
	v_add_f32_e32 v252, v81, v83
	v_exp_f32_e32 v86, v86
	v_add_f32_e32 v205, v205, v84
	v_exp_f32_e32 v87, v87
	v_add_f32_e32 v252, v252, v85
	v_exp_f32_e32 v88, v88
	s_waitcnt lgkmcnt(3)
	v_mfma_f32_32x32x16_bf16 v[112:127], v[32:35], v[148:151], v[48:63]
	ds_read_b128 v[32:35], v242 offset:6720
	v_add_f32_e32 v205, v205, v86
	v_exp_f32_e32 v89, v89
	v_add_f32_e32 v252, v252, v87
	v_cvt_pk_bf16_f32 v80, v80, v81
	v_cvt_pk_bf16_f32 v81, v82, v83
	v_mfma_f32_32x32x16_bf16 v[64:79], v[36:39], v[148:151], v[48:63]
	ds_read_b128 v[36:39], v242 offset:96
	v_cvt_pk_bf16_f32 v82, v84, v85
	v_cvt_pk_bf16_f32 v83, v86, v87
	v_exp_f32_e32 v90, v90
	v_add_f32_e32 v205, v205, v88
	v_exp_f32_e32 v91, v91
	s_waitcnt lgkmcnt(3)
	v_mfma_f32_32x32x16_bf16 v[112:127], v[40:43], v[144:147], v[112:127]
	ds_read_b128 v[40:43], v242 offset:6752
	v_add_f32_e32 v252, v252, v89
	v_exp_f32_e32 v92, v92
	v_add_f32_e32 v205, v205, v90
	v_exp_f32_e32 v93, v93
	v_add_f32_e32 v252, v252, v91
	v_mfma_f32_32x32x16_bf16 v[64:79], v[44:47], v[144:147], v[64:79]
	ds_read_b128 v[44:47], v242 offset:128
	v_exp_f32_e32 v94, v94
	v_add_f32_e32 v205, v205, v92
	v_exp_f32_e32 v95, v95
	v_add_f32_e32 v252, v252, v93
	v_exp_f32_e32 v96, v96
	s_waitcnt lgkmcnt(3)
	v_mfma_f32_32x32x16_bf16 v[112:127], v[238:241], v[140:143], v[112:127]
	ds_read_b128 v[238:241], v242 offset:6784
	v_add_f32_e32 v205, v205, v94
	v_exp_f32_e32 v97, v97
	v_add_f32_e32 v252, v252, v95
	v_cvt_pk_bf16_f32 v88, v88, v89
	v_cvt_pk_bf16_f32 v89, v90, v91
	v_mfma_f32_32x32x16_bf16 v[64:79], v[32:35], v[140:143], v[64:79]
	ds_read_b128 v[32:35], v242 offset:160
	v_cvt_pk_bf16_f32 v90, v92, v93
	v_cvt_pk_bf16_f32 v91, v94, v95
	v_exp_f32_e32 v98, v98
	v_add_f32_e32 v205, v205, v96
	v_exp_f32_e32 v99, v99
	v_add_f32_e32 v252, v252, v97
	s_waitcnt lgkmcnt(3)
	v_mfma_f32_32x32x16_bf16 v[112:127], v[36:39], v[136:139], v[112:127]
	ds_read_b128 v[36:39], v242 offset:6816
	v_exp_f32_e32 v100, v100
	v_add_f32_e32 v205, v205, v98
	v_exp_f32_e32 v101, v101
	v_add_f32_e32 v252, v252, v99
	v_exp_f32_e32 v102, v102
	v_add_f32_e32 v205, v205, v100
	v_mfma_f32_32x32x16_bf16 v[64:79], v[40:43], v[136:139], v[64:79]
	ds_read_b64_tr_b16 v[40:41], v243 offset:13312
	ds_read_b64_tr_b16 v[42:43], v243 offset:14848
	v_exp_f32_e32 v103, v103
	v_add_f32_e32 v252, v252, v101
	v_exp_f32_e32 v104, v104
	v_add_f32_e32 v205, v205, v102
	v_exp_f32_e32 v105, v105
	v_add_f32_e32 v252, v252, v103
	s_waitcnt lgkmcnt(4)
	v_mfma_f32_32x32x16_bf16 v[112:127], v[44:47], v[132:135], v[112:127]
	ds_read_b64_tr_b16 v[44:45], v243 offset:13376
	ds_read_b64_tr_b16 v[46:47], v243 offset:14912
	v_cvt_pk_bf16_f32 v96, v96, v97
	v_cvt_pk_bf16_f32 v97, v98, v99
	v_cvt_pk_bf16_f32 v98, v100, v101
	v_cvt_pk_bf16_f32 v99, v102, v103
	v_exp_f32_e32 v106, v106
	v_add_f32_e32 v205, v205, v104
	v_mfma_f32_32x32x16_bf16 v[64:79], v[238:241], v[132:135], v[64:79]
	ds_read_b64_tr_b16 v[238:239], v243 offset:16384
	ds_read_b64_tr_b16 v[240:241], v243 offset:17920
	v_exp_f32_e32 v107, v107
	v_add_f32_e32 v252, v252, v105
	v_exp_f32_e32 v108, v108
	v_add_f32_e32 v205, v205, v106
	v_exp_f32_e32 v109, v109
	v_add_f32_e32 v252, v252, v107
	s_waitcnt lgkmcnt(6)
	v_mfma_f32_32x32x16_bf16 v[112:127], v[32:35], v[128:131], v[112:127]
	ds_read_b64_tr_b16 v[32:33], v243 offset:16448
	ds_read_b64_tr_b16 v[34:35], v243 offset:17984
	v_exp_f32_e32 v110, v110
	v_add_f32_e32 v205, v205, v108
	v_exp_f32_e32 v111, v111
	v_add_f32_e32 v252, v252, v109
	v_add_f32_e32 v205, v205, v110
	v_add_f32_e32 v252, v252, v111
	v_mfma_f32_32x32x16_bf16 v[64:79], v[36:39], v[128:131], v[64:79]
	ds_read_b64_tr_b16 v[36:37], v243 offset:19456
	ds_read_b64_tr_b16 v[38:39], v243 offset:20992
	v_cvt_pk_bf16_f32 v104, v104, v105
	v_cvt_pk_bf16_f32 v105, v106, v107
	v_cvt_pk_bf16_f32 v106, v108, v109
	v_cvt_pk_bf16_f32 v107, v110, v111
	v_add_f32_e32 v205, v205, v252
	s_waitcnt lgkmcnt(6)
	v_mfma_f32_32x32x16_bf16 v[0:15], v[80:83], v[40:43], v[0:15]
	ds_read_b64_tr_b16 v[40:41], v243 offset:19520
	ds_read_b64_tr_b16 v[42:43], v243 offset:21056
	v_mfma_f32_32x32x16_bf16 v[16:31], v[80:83], v[44:47], v[16:31]
	ds_read_b64_tr_b16 v[44:45], v243 offset:22528
	ds_read_b64_tr_b16 v[46:47], v243 offset:24064
	s_waitcnt lgkmcnt(6)
	v_mfma_f32_32x32x16_bf16 v[0:15], v[88:91], v[238:241], v[0:15]
	ds_read_b64_tr_b16 v[238:239], v243 offset:22592
	ds_read_b64_tr_b16 v[240:241], v243 offset:24128
	v_max_f32_e32 v191, v112, v113
	v_max_f32_e32 v178, v64, v65
	v_max3_f32 v191, v191, v114, v115
	v_max3_f32 v178, v178, v66, v67
	v_mfma_f32_32x32x16_bf16 v[16:31], v[88:91], v[32:35], v[16:31]
	v_add_u32_e32 v242, s7, v215
	ds_read_b128 v[32:35], v242
	v_max3_f32 v191, v191, v116, v117
	v_max3_f32 v178, v178, v68, v69
	v_max3_f32 v191, v191, v118, v119
	v_max3_f32 v178, v178, v70, v71
	s_waitcnt lgkmcnt(5)
	v_mfma_f32_32x32x16_bf16 v[0:15], v[96:99], v[36:39], v[0:15]
	ds_read_b128 v[36:39], v242 offset:6656
	v_max3_f32 v191, v191, v120, v121
	v_max3_f32 v178, v178, v72, v73
	v_max3_f32 v191, v191, v122, v123
	v_max3_f32 v178, v178, v74, v75
	v_mfma_f32_32x32x16_bf16 v[16:31], v[96:99], v[40:43], v[16:31]
	ds_read_b128 v[40:43], v242 offset:32
	v_max3_f32 v191, v191, v124, v125
	v_max3_f32 v178, v178, v76, v77
	v_max3_f32 v191, v191, v126, v127
	v_max3_f32 v178, v178, v78, v79
	s_waitcnt lgkmcnt(3)
	v_mfma_f32_32x32x16_bf16 v[0:15], v[104:107], v[44:47], v[0:15]
	ds_read_b128 v[44:47], v242 offset:6688
	v_max_f32_e32 v212, v191, v178
	v_mov_b32_e32 v253, v212
	v_mfma_f32_32x32x16_bf16 v[16:31], v[104:107], v[238:241], v[16:31]
	ds_read_b128 v[238:241], v242 offset:64
	s_nop 0
	v_permlane32_swap_b32_e32 v212, v253
	v_max_f32_e32 v212, v212, v253
	v_cmp_lt_f32_e32 vcc, s58, v212
	s_cbranch_vccz .Lmla_skip_a
	s_nop 1
	v_cndmask_b32_e32 v100, 0, v212, vcc
	v_exp_f32_e64 v102, -v100
	v_add_f32_e32 v203, v203, v100
	v_xor_b32_e32 v101, 0x80000000, v203
	ds_bpermute_b32 v84, v217, v102
	ds_bpermute_b32 v85, v218, v102
	ds_bpermute_b32 v86, v219, v102
	ds_bpermute_b32 v87, v220, v102
	ds_bpermute_b32 v88, v221, v102
	ds_bpermute_b32 v89, v222, v102
	ds_bpermute_b32 v90, v223, v102
	ds_bpermute_b32 v91, v224, v102
	ds_bpermute_b32 v92, v225, v102
	ds_bpermute_b32 v93, v226, v102
	ds_bpermute_b32 v94, v227, v102
	ds_bpermute_b32 v95, v228, v102
	ds_bpermute_b32 v96, v229, v102
	ds_bpermute_b32 v97, v230, v102
	ds_bpermute_b32 v98, v231, v102
	ds_bpermute_b32 v99, v232, v102
	v_sub_f32_e32 v112, v112, v100
	v_sub_f32_e32 v113, v113, v100
	v_sub_f32_e32 v114, v114, v100
	v_sub_f32_e32 v115, v115, v100
	v_sub_f32_e32 v116, v116, v100
	v_sub_f32_e32 v117, v117, v100
	v_sub_f32_e32 v118, v118, v100
	v_sub_f32_e32 v119, v119, v100
	v_sub_f32_e32 v120, v120, v100
	v_sub_f32_e32 v121, v121, v100
	v_sub_f32_e32 v122, v122, v100
	v_sub_f32_e32 v123, v123, v100
	v_sub_f32_e32 v124, v124, v100
	v_sub_f32_e32 v125, v125, v100
	v_sub_f32_e32 v126, v126, v100
	v_sub_f32_e32 v127, v127, v100
	v_sub_f32_e32 v64, v64, v100
	v_sub_f32_e32 v65, v65, v100
	v_sub_f32_e32 v66, v66, v100
	v_sub_f32_e32 v67, v67, v100
	v_sub_f32_e32 v68, v68, v100
	v_sub_f32_e32 v69, v69, v100
	v_sub_f32_e32 v70, v70, v100
	v_sub_f32_e32 v71, v71, v100
	v_sub_f32_e32 v72, v72, v100
	v_sub_f32_e32 v73, v73, v100
	v_sub_f32_e32 v74, v74, v100
	v_sub_f32_e32 v75, v75, v100
	v_sub_f32_e32 v76, v76, v100
	v_sub_f32_e32 v77, v77, v100
	v_sub_f32_e32 v78, v78, v100
	v_sub_f32_e32 v79, v79, v100
	v_mul_f32_e32 v205, v205, v102
	v_mov_b32_e32 v48, v101
	v_mov_b32_e32 v49, v101
	v_mov_b32_e32 v50, v101
	v_mov_b32_e32 v51, v101
	v_mov_b32_e32 v52, v101
	v_mov_b32_e32 v53, v101
	v_mov_b32_e32 v54, v101
	v_mov_b32_e32 v55, v101
	v_mov_b32_e32 v56, v101
	v_mov_b32_e32 v57, v101
	v_mov_b32_e32 v58, v101
	v_mov_b32_e32 v59, v101
	v_mov_b32_e32 v60, v101
	v_mov_b32_e32 v61, v101
	v_mov_b32_e32 v62, v101
	v_mov_b32_e32 v63, v101
	s_waitcnt lgkmcnt(0)
	v_pk_mul_f32 v[0:1], v[0:1], v[84:85]
	v_pk_mul_f32 v[16:17], v[16:17], v[84:85]
	v_pk_mul_f32 v[2:3], v[2:3], v[86:87]
	v_pk_mul_f32 v[18:19], v[18:19], v[86:87]
	v_pk_mul_f32 v[4:5], v[4:5], v[88:89]
	v_pk_mul_f32 v[20:21], v[20:21], v[88:89]
	v_pk_mul_f32 v[6:7], v[6:7], v[90:91]
	v_pk_mul_f32 v[22:23], v[22:23], v[90:91]
	v_pk_mul_f32 v[8:9], v[8:9], v[92:93]
	v_pk_mul_f32 v[24:25], v[24:25], v[92:93]
	v_pk_mul_f32 v[10:11], v[10:11], v[94:95]
	v_pk_mul_f32 v[26:27], v[26:27], v[94:95]
	v_pk_mul_f32 v[12:13], v[12:13], v[96:97]
	v_pk_mul_f32 v[28:29], v[28:29], v[96:97]
	v_pk_mul_f32 v[14:15], v[14:15], v[98:99]
	v_pk_mul_f32 v[30:31], v[30:31], v[98:99]
.Lmla_skip_a:
	v_add_u32_e32 v177, s6, v185
	s_waitcnt vmcnt(5)
	ds_write_b128 v177, v[152:155]
	v_add_u32_e32 v177, v177, v181
	s_waitcnt vmcnt(4)
	ds_write_b128 v177, v[156:159]
	v_mov_b32_e32 v177, s6
	v_cndmask_b32_e64 v177, 0, v177, s[4:5]
	v_add_u32_e32 v177, v214, v177
	s_waitcnt vmcnt(3)
	ds_write_b128 v177, v[160:163]
	v_add_u32_e32 v243, s10, v233
	s_min_u32 s8, s9, 58
	s_lshl_b32 s8, s8, 6
	s_addk_i32 s8, 0x140
	s_lshl_b32 s76, s8, 12
	v_lshl_add_u64 v[152:153], v[206:207], 0, s[76:77]
	v_add_co_u32_e32 v156, vcc, s83, v152
	s_lshl_b32 s76, s8, 6
	s_nop 0
	v_addc_co_u32_e32 v157, vcc, 0, v153, vcc
	global_load_dwordx4 v[152:155], v[152:153], off
	v_lshl_add_u64 v[160:161], v[208:209], 0, s[76:77]
	global_load_dwordx4 v[156:159], v[156:157], off
	global_load_dwordx4 v[160:163], v[160:161], off
	s_waitcnt lgkmcnt(6)
	v_mfma_f32_32x32x16_bf16 v[80:95], v[32:35], v[148:151], v[48:63]
	ds_read_b128 v[32:35], v242 offset:6720
	v_exp_f32_e32 v112, v112
	v_exp_f32_e32 v113, v113
	v_exp_f32_e32 v114, v114
	v_add_f32_e32 v205, v205, v112
	v_exp_f32_e32 v115, v115
	v_exp_f32_e32 v116, v116
	v_mfma_f32_32x32x16_bf16 v[96:111], v[36:39], v[148:151], v[48:63]
	ds_read_b128 v[36:39], v242 offset:96
	v_add_f32_e32 v205, v205, v114
	v_exp_f32_e32 v117, v117
	v_add_f32_e32 v252, v113, v115
	v_exp_f32_e32 v118, v118
	v_add_f32_e32 v205, v205, v116
	v_exp_f32_e32 v119, v119
	v_add_f32_e32 v252, v252, v117
	s_waitcnt lgkmcnt(6)
	v_mfma_f32_32x32x16_bf16 v[80:95], v[40:43], v[144:147], v[80:95]
	ds_read_b128 v[40:43], v242 offset:6752
	v_exp_f32_e32 v120, v120
	v_add_f32_e32 v205, v205, v118
	v_exp_f32_e32 v121, v121
	v_add_f32_e32 v252, v252, v119
	v_cvt_pk_bf16_f32 v112, v112, v113
	v_cvt_pk_bf16_f32 v113, v114, v115
	v_cvt_pk_bf16_f32 v114, v116, v117
	v_mfma_f32_32x32x16_bf16 v[96:111], v[44:47], v[144:147], v[96:111]
	ds_read_b128 v[44:47], v242 offset:128
	v_cvt_pk_bf16_f32 v115, v118, v119
	v_exp_f32_e32 v122, v122
	v_add_f32_e32 v205, v205, v120
	v_exp_f32_e32 v123, v123
	v_add_f32_e32 v252, v252, v121
	v_exp_f32_e32 v124, v124
	v_add_f32_e32 v205, v205, v122
	s_waitcnt lgkmcnt(3)
	v_mfma_f32_32x32x16_bf16 v[80:95], v[238:241], v[140:143], v[80:95]
	ds_read_b128 v[238:241], v242 offset:6784
	v_exp_f32_e32 v125, v125
	v_add_f32_e32 v252, v252, v123
	v_exp_f32_e32 v126, v126
	v_add_f32_e32 v205, v205, v124
	v_exp_f32_e32 v127, v127
	v_add_f32_e32 v252, v252, v125
	v_exp_f32_e32 v64, v64
	v_mfma_f32_32x32x16_bf16 v[96:111], v[32:35], v[140:143], v[96:111]
	ds_read_b128 v[32:35], v242 offset:160
	v_add_f32_e32 v205, v205, v126
	v_exp_f32_e32 v65, v65
	v_add_f32_e32 v252, v252, v127
	v_cvt_pk_bf16_f32 v120, v120, v121
	v_cvt_pk_bf16_f32 v121, v122, v123
	v_cvt_pk_bf16_f32 v122, v124, v125
	v_cvt_pk_bf16_f32 v123, v126, v127
	s_waitcnt lgkmcnt(3)
	v_mfma_f32_32x32x16_bf16 v[80:95], v[36:39], v[136:139], v[80:95]
	ds_read_b128 v[36:39], v242 offset:6816
	v_exp_f32_e32 v66, v66
	v_add_f32_e32 v205, v205, v64
	v_exp_f32_e32 v67, v67
	v_add_f32_e32 v252, v252, v65
	v_exp_f32_e32 v68, v68
	v_add_f32_e32 v205, v205, v66
	v_exp_f32_e32 v69, v69
	v_mfma_f32_32x32x16_bf16 v[96:111], v[40:43], v[136:139], v[96:111]
	ds_read_b64_tr_b16 v[40:41], v243 offset:13312
	ds_read_b64_tr_b16 v[42:43], v243 offset:14848
	v_add_f32_e32 v252, v252, v67
	v_exp_f32_e32 v70, v70
	v_add_f32_e32 v205, v205, v68
	v_exp_f32_e32 v71, v71
	v_add_f32_e32 v252, v252, v69
	v_exp_f32_e32 v72, v72
	v_add_f32_e32 v205, v205, v70
	s_waitcnt lgkmcnt(4)
	v_mfma_f32_32x32x16_bf16 v[80:95], v[44:47], v[132:135], v[80:95]
	ds_read_b64_tr_b16 v[44:45], v243 offset:13376
	ds_read_b64_tr_b16 v[46:47], v243 offset:14912
	v_exp_f32_e32 v73, v73
	v_add_f32_e32 v252, v252, v71
	v_cvt_pk_bf16_f32 v64, v64, v65
	v_cvt_pk_bf16_f32 v65, v66, v67
	v_cvt_pk_bf16_f32 v66, v68, v69
	v_cvt_pk_bf16_f32 v67, v70, v71
	v_exp_f32_e32 v74, v74
	v_mfma_f32_32x32x16_bf16 v[96:111], v[238:241], v[132:135], v[96:111]
	ds_read_b64_tr_b16 v[238:239], v243 offset:16384
	ds_read_b64_tr_b16 v[240:241], v243 offset:17920
	v_add_f32_e32 v205, v205, v72
	v_exp_f32_e32 v75, v75
	v_add_f32_e32 v252, v252, v73
	v_exp_f32_e32 v76, v76
	v_add_f32_e32 v205, v205, v74
	v_exp_f32_e32 v77, v77
	v_add_f32_e32 v252, v252, v75
	s_waitcnt lgkmcnt(6)
	v_mfma_f32_32x32x16_bf16 v[80:95], v[32:35], v[128:131], v[80:95]
	ds_read_b64_tr_b16 v[32:33], v243 offset:16448
	ds_read_b64_tr_b16 v[34:35], v243 offset:17984
	v_exp_f32_e32 v78, v78
	v_add_f32_e32 v205, v205, v76
	v_exp_f32_e32 v79, v79
	v_add_f32_e32 v252, v252, v77
	v_add_f32_e32 v205, v205, v78
	v_add_f32_e32 v252, v252, v79
	v_cvt_pk_bf16_f32 v72, v72, v73
	v_mfma_f32_32x32x16_bf16 v[96:111], v[36:39], v[128:131], v[96:111]
	ds_read_b64_tr_b16 v[36:37], v243 offset:19456
	ds_read_b64_tr_b16 v[38:39], v243 offset:20992
	v_cvt_pk_bf16_f32 v73, v74, v75
	v_cvt_pk_bf16_f32 v74, v76, v77
	v_cvt_pk_bf16_f32 v75, v78, v79
	v_add_f32_e32 v205, v205, v252
	s_waitcnt lgkmcnt(6)
	v_mfma_f32_32x32x16_bf16 v[0:15], v[112:115], v[40:43], v[0:15]
	ds_read_b64_tr_b16 v[40:41], v243 offset:19520
	ds_read_b64_tr_b16 v[42:43], v243 offset:21056
	v_mfma_f32_32x32x16_bf16 v[16:31], v[112:115], v[44:47], v[16:31]
	ds_read_b64_tr_b16 v[44:45], v243 offset:22528
	ds_read_b64_tr_b16 v[46:47], v243 offset:24064
	s_waitcnt lgkmcnt(6)
	v_mfma_f32_32x32x16_bf16 v[0:15], v[120:123], v[238:241], v[0:15]
	ds_read_b64_tr_b16 v[238:239], v243 offset:22592
	ds_read_b64_tr_b16 v[240:241], v243 offset:24128
	v_max_f32_e32 v191, v80, v81
	v_max_f32_e32 v178, v96, v97
	v_max3_f32 v191, v191, v82, v83
	v_max3_f32 v178, v178, v98, v99
	v_mfma_f32_32x32x16_bf16 v[16:31], v[120:123], v[32:35], v[16:31]
	v_max3_f32 v191, v191, v84, v85
	v_max3_f32 v178, v178, v100, v101
	v_max3_f32 v191, v191, v86, v87
	v_max3_f32 v178, v178, v102, v103
	s_waitcnt lgkmcnt(4)
	v_mfma_f32_32x32x16_bf16 v[0:15], v[64:67], v[36:39], v[0:15]
	v_max3_f32 v191, v191, v88, v89
	v_max3_f32 v178, v178, v104, v105
	v_max3_f32 v191, v191, v90, v91
	v_max3_f32 v178, v178, v106, v107
	v_mfma_f32_32x32x16_bf16 v[16:31], v[64:67], v[40:43], v[16:31]
	v_max3_f32 v191, v191, v92, v93
	v_max3_f32 v178, v178, v108, v109
	v_max3_f32 v191, v191, v94, v95
	v_max3_f32 v178, v178, v110, v111
	s_waitcnt lgkmcnt(0)
	v_mfma_f32_32x32x16_bf16 v[0:15], v[72:75], v[44:47], v[0:15]
	v_max_f32_e32 v212, v191, v178
	v_mov_b32_e32 v253, v212
	v_mfma_f32_32x32x16_bf16 v[16:31], v[72:75], v[238:241], v[16:31]
	s_nop 0
	v_permlane32_swap_b32_e32 v212, v253
	v_max_f32_e32 v212, v212, v253
	v_cmp_lt_f32_e32 vcc, s58, v212
	s_cbranch_vccz .Lmla_skip_b
	s_nop 1
	v_cndmask_b32_e32 v68, 0, v212, vcc
	v_exp_f32_e64 v70, -v68
	v_add_f32_e32 v203, v203, v68
	v_xor_b32_e32 v69, 0x80000000, v203
	ds_bpermute_b32 v116, v217, v70
	ds_bpermute_b32 v117, v218, v70
	ds_bpermute_b32 v118, v219, v70
	ds_bpermute_b32 v119, v220, v70
	ds_bpermute_b32 v120, v221, v70
	ds_bpermute_b32 v121, v222, v70
	ds_bpermute_b32 v122, v223, v70
	ds_bpermute_b32 v123, v224, v70
	ds_bpermute_b32 v124, v225, v70
	ds_bpermute_b32 v125, v226, v70
	ds_bpermute_b32 v126, v227, v70
	ds_bpermute_b32 v127, v228, v70
	ds_bpermute_b32 v64, v229, v70
	ds_bpermute_b32 v65, v230, v70
	ds_bpermute_b32 v66, v231, v70
	ds_bpermute_b32 v67, v232, v70
	v_sub_f32_e32 v80, v80, v68
	v_sub_f32_e32 v81, v81, v68
	v_sub_f32_e32 v82, v82, v68
	v_sub_f32_e32 v83, v83, v68
	v_sub_f32_e32 v84, v84, v68
	v_sub_f32_e32 v85, v85, v68
	v_sub_f32_e32 v86, v86, v68
	v_sub_f32_e32 v87, v87, v68
	v_sub_f32_e32 v88, v88, v68
	v_sub_f32_e32 v89, v89, v68
	v_sub_f32_e32 v90, v90, v68
	v_sub_f32_e32 v91, v91, v68
	v_sub_f32_e32 v92, v92, v68
	v_sub_f32_e32 v93, v93, v68
	v_sub_f32_e32 v94, v94, v68
	v_sub_f32_e32 v95, v95, v68
	v_sub_f32_e32 v96, v96, v68
	v_sub_f32_e32 v97, v97, v68
	v_sub_f32_e32 v98, v98, v68
	v_sub_f32_e32 v99, v99, v68
	v_sub_f32_e32 v100, v100, v68
	v_sub_f32_e32 v101, v101, v68
	v_sub_f32_e32 v102, v102, v68
	v_sub_f32_e32 v103, v103, v68
	v_sub_f32_e32 v104, v104, v68
	v_sub_f32_e32 v105, v105, v68
	v_sub_f32_e32 v106, v106, v68
	v_sub_f32_e32 v107, v107, v68
	v_sub_f32_e32 v108, v108, v68
	v_sub_f32_e32 v109, v109, v68
	v_sub_f32_e32 v110, v110, v68
	v_sub_f32_e32 v111, v111, v68
	v_mul_f32_e32 v205, v205, v70
	v_mov_b32_e32 v48, v69
	v_mov_b32_e32 v49, v69
	v_mov_b32_e32 v50, v69
	v_mov_b32_e32 v51, v69
	v_mov_b32_e32 v52, v69
	v_mov_b32_e32 v53, v69
	v_mov_b32_e32 v54, v69
	v_mov_b32_e32 v55, v69
	v_mov_b32_e32 v56, v69
	v_mov_b32_e32 v57, v69
	v_mov_b32_e32 v58, v69
	v_mov_b32_e32 v59, v69
	v_mov_b32_e32 v60, v69
	v_mov_b32_e32 v61, v69
	v_mov_b32_e32 v62, v69
	v_mov_b32_e32 v63, v69
	s_waitcnt lgkmcnt(0)
	v_pk_mul_f32 v[0:1], v[0:1], v[116:117]
	v_pk_mul_f32 v[16:17], v[16:17], v[116:117]
	v_pk_mul_f32 v[2:3], v[2:3], v[118:119]
	v_pk_mul_f32 v[18:19], v[18:19], v[118:119]
	v_pk_mul_f32 v[4:5], v[4:5], v[120:121]
	v_pk_mul_f32 v[20:21], v[20:21], v[120:121]
	v_pk_mul_f32 v[6:7], v[6:7], v[122:123]
	v_pk_mul_f32 v[22:23], v[22:23], v[122:123]
	v_pk_mul_f32 v[8:9], v[8:9], v[124:125]
	v_pk_mul_f32 v[24:25], v[24:25], v[124:125]
	v_pk_mul_f32 v[10:11], v[10:11], v[126:127]
	v_pk_mul_f32 v[26:27], v[26:27], v[126:127]
	v_pk_mul_f32 v[12:13], v[12:13], v[64:65]
	v_pk_mul_f32 v[28:29], v[28:29], v[64:65]
	v_pk_mul_f32 v[14:15], v[14:15], v[66:67]
	v_pk_mul_f32 v[30:31], v[30:31], v[66:67]
